# v28 + nt policy on the prologue loads of x (read once)
# speedup vs baseline: 1.0175x; 1.0140x over previous
; __device__ __forceinline__ unsigned pk2(float lo, float hi) { return pg8::cvt_pk_bf16(lo, hi); }
; __device__ __forceinline__ void prologue(const Args& a, LAS unsigned char* lds, int G, int bid) {
;     ...
;     for (int m = gw; m < SEQ; m += NGW) {
;         const f32x4* xr = (const f32x4*)(x + (size_t)m * DM) + lane; f32x4 v[8]; float s = 0.f;
; #pragma unroll
;         for (int j = 0; j < 8; ++j) { v[j] = xr[64 * j]; s += (v[j][0] * v[j][0] + v[j][1] * v[j][1]) + (v[j][2] * v[j][2] + v[j][3] * v[j][3]); }
;         s = wave_sum(s);
;         v2u* o8 = (v2u*)(XB + (size_t)m * DM) + lane;
; #pragma unroll
;         for (int j = 0; j < 8; ++j) { v2u w; w.x = pk2(v[j][0], v[j][1]); w.y = pk2(v[j][2], v[j][3]); o8[64 * j] = w; }
;         if (lane < 8) ss[(size_t)m * 8 + lane] = (lane == 0) ? s : 0.f;
;     }
.LBB0_603:
	s_waitcnt lgkmcnt(0)
	global_load_dwordx4 v[18:21], v[10:11], off offset:-4096 nt
	global_load_dwordx4 v[22:25], v[10:11], off offset:-3072 nt
	global_load_dwordx4 v[26:29], v[10:11], off offset:-2048 nt
	global_load_dwordx4 v[30:33], v[10:11], off offset:-1024 nt
	global_load_dwordx4 v[34:37], v[10:11], off nt
	global_load_dwordx4 v[38:41], v[10:11], off offset:1024 nt
	global_load_dwordx4 v[42:45], v[10:11], off offset:2048 nt
	global_load_dwordx4 v[46:49], v[10:11], off offset:3072 nt
	s_waitcnt vmcnt(7)
	v_mul_f32_e32 v0, v19, v19
	v_mul_f32_e32 v50, v21, v21
	s_waitcnt vmcnt(6)
	v_mul_f32_e32 v51, v23, v23
	v_mul_f32_e32 v52, v25, v25
	s_waitcnt vmcnt(5)
	v_mul_f32_e32 v53, v27, v27
	v_mul_f32_e32 v54, v29, v29
	v_fmac_f32_e32 v0, v18, v18
	v_fmac_f32_e32 v50, v20, v20
	v_fmac_f32_e32 v51, v22, v22
	v_fmac_f32_e32 v52, v24, v24
	s_waitcnt vmcnt(4)
	v_mul_f32_e32 v55, v31, v31
	v_mul_f32_e32 v56, v33, v33
	v_fmac_f32_e32 v53, v26, v26
	v_fmac_f32_e32 v54, v28, v28
	v_add_f32_e32 v0, v0, v50
	v_add_f32_e32 v50, v51, v52
	s_waitcnt vmcnt(3)
	v_mul_f32_e32 v57, v35, v35
	v_mul_f32_e32 v58, v37, v37
	v_fmac_f32_e32 v55, v30, v30
	v_fmac_f32_e32 v56, v32, v32
	v_add_f32_e32 v51, v53, v54
	v_add_f32_e32 v0, v0, v50
	s_waitcnt vmcnt(2)
	v_mul_f32_e32 v59, v39, v39
	v_mul_f32_e32 v60, v41, v41
	v_fmac_f32_e32 v57, v34, v34
	v_fmac_f32_e32 v58, v36, v36
	v_add_f32_e32 v52, v55, v56
	v_add_f32_e32 v0, v0, v51
	s_waitcnt vmcnt(1)
	v_mul_f32_e32 v61, v43, v43
	v_mul_f32_e32 v62, v45, v45
	v_fmac_f32_e32 v59, v38, v38
	v_fmac_f32_e32 v60, v40, v40
	v_add_f32_e32 v53, v57, v58
	v_add_f32_e32 v0, v0, v52
	s_waitcnt vmcnt(0)
	v_mul_f32_e32 v63, v47, v47
	v_mul_f32_e32 v64, v49, v49
	v_fmac_f32_e32 v61, v42, v42
	v_fmac_f32_e32 v62, v44, v44
	v_add_f32_e32 v54, v59, v60
	v_add_f32_e32 v0, v0, v53
	v_fmac_f32_e32 v63, v46, v46
	v_fmac_f32_e32 v64, v48, v48
	v_add_f32_e32 v55, v61, v62
	v_add_f32_e32 v0, v0, v54
	v_add_f32_e32 v56, v63, v64
	v_add_f32_e32 v0, v0, v55
	v_add_f32_e32 v0, v0, v56
	ds_bpermute_b32 v50, v12, v0
	v_cvt_pk_bf16_f32 v18, v18, v19
	v_cvt_pk_bf16_f32 v19, v20, v21
	global_store_dwordx2 v[2:3], v[18:19], off offset:-2048
	v_cvt_pk_bf16_f32 v18, v22, v23
	s_waitcnt lgkmcnt(0)
	v_add_f32_e32 v0, v0, v50
	ds_bpermute_b32 v20, v13, v0
	v_cvt_pk_bf16_f32 v19, v24, v25
	global_store_dwordx2 v[2:3], v[18:19], off offset:-1536
	v_cvt_pk_bf16_f32 v18, v26, v27
	v_cvt_pk_bf16_f32 v19, v28, v29
	s_waitcnt lgkmcnt(0)
	v_add_f32_e32 v0, v0, v20
	ds_bpermute_b32 v20, v14, v0
	global_store_dwordx2 v[2:3], v[18:19], off offset:-1024
	v_cvt_pk_bf16_f32 v18, v30, v31
	v_cvt_pk_bf16_f32 v19, v32, v33
	global_store_dwordx2 v[2:3], v[18:19], off offset:-512
	s_waitcnt lgkmcnt(0)
	v_add_f32_e32 v0, v0, v20
	ds_bpermute_b32 v20, v15, v0
	v_cvt_pk_bf16_f32 v18, v34, v35
	v_cvt_pk_bf16_f32 v19, v36, v37
	global_store_dwordx2 v[2:3], v[18:19], off
	v_cvt_pk_bf16_f32 v18, v38, v39
	s_waitcnt lgkmcnt(0)
	v_add_f32_e32 v0, v0, v20
	ds_bpermute_b32 v21, v16, v0
	v_cvt_pk_bf16_f32 v19, v40, v41
	global_store_dwordx2 v[2:3], v[18:19], off offset:512
	v_cvt_pk_bf16_f32 v20, v42, v43
	s_waitcnt lgkmcnt(0)
	v_add_f32_e32 v0, v0, v21
	ds_bpermute_b32 v18, v17, v0
	v_cvt_pk_bf16_f32 v21, v44, v45
	global_store_dwordx2 v[2:3], v[20:21], off offset:1024
	v_cvt_pk_bf16_f32 v20, v46, v47
	v_cvt_pk_bf16_f32 v21, v48, v49
	global_store_dwordx2 v[2:3], v[20:21], off offset:1536
	s_and_saveexec_b64 s[0:1], vcc
	s_cbranch_execz .LBB0_602
	s_waitcnt lgkmcnt(0)
	v_add_f32_e32 v0, v0, v18
	v_cndmask_b32_e64 v0, 0, v0, s[2:3]
	global_store_dword v[8:9], v0, off
	s_branch .LBB0_602
